# speedup vs baseline: 1.0056x; 1.0011x over previous
; __device__ __forceinline__ unsigned xb_ld(unsigned* p)              { return __hip_atomic_load(p, __ATOMIC_RELAXED, __HIP_MEMORY_SCOPE_AGENT); }
; __device__ __forceinline__ void xcd_barrier_complete(unsigned* bar, unsigned x, unsigned& nloc, unsigned& nx) {
;     ...
;     for (;;) {
;         sum = 0u; cnt = 0u; mine = 0u;
; #pragma unroll
;         for (unsigned j = 0; j < 16; ++j) { const unsigned c = xb_ld(&bar[XB_XCNT(j)]); sum += c; cnt += (c > 0u) ? 1u : 0u; mine = (j == x) ? c : mine; }
;         if (sum == G) break;
;         __builtin_amdgcn_s_sleep(1);
;         if ((++sp & 255u) == 0u) { if (xb_ld(&bar[XB_TMO])) break; if (sp > XB_SPIN_CAP) { atomicAdd(&bar[XB_TMO], 1u); break; } }
.LBB0_186:
	v_mov_b32_e32 v17, 0
	s_waitcnt lgkmcnt(0)
	global_load_dword v0, v17, s[6:7] sc1
	global_load_dword v2, v17, s[8:9] sc1
	global_load_dword v3, v17, s[10:11] sc1
	global_load_dword v4, v17, s[12:13] sc1
	global_load_dword v5, v17, s[14:15] sc1
	global_load_dword v6, v17, s[16:17] sc1
	global_load_dword v7, v17, s[18:19] sc1
	global_load_dword v8, v17, s[20:21] sc1
	global_load_dword v9, v17, s[22:23] sc1
	global_load_dword v10, v17, s[24:25] sc1
	global_load_dword v11, v17, s[26:27] sc1
	global_load_dword v12, v17, s[28:29] sc1
	global_load_dword v13, v17, s[30:31] sc1
	global_load_dword v14, v17, s[34:35] sc1
	global_load_dword v15, v17, s[38:39] sc1
	global_load_dword v16, v17, s[40:41] sc1
	v_readlane_b32 s0, v252, 38
	s_or_b64 s[60:61], s[60:61], exec
	s_or_b64 s[54:55], s[54:55], exec
	s_waitcnt vmcnt(0)
	v_add_u32_e32 v17, v2, v0
	v_add_u32_e32 v17, v17, v3
	v_add_u32_e32 v17, v17, v4
	v_add_u32_e32 v17, v17, v5
	v_add_u32_e32 v17, v17, v6
	v_add_u32_e32 v17, v17, v7
	v_add_u32_e32 v17, v17, v8
	v_add_u32_e32 v17, v17, v9
	v_add_u32_e32 v17, v17, v10
	v_add_u32_e32 v17, v17, v11
	v_add_u32_e32 v17, v17, v12
	v_add_u32_e32 v17, v17, v13
	v_add_u32_e32 v17, v17, v14
	v_add_u32_e32 v17, v17, v15
	v_add_u32_e32 v17, v17, v16
	v_cmp_ne_u32_e32 vcc, s0, v17
	s_and_saveexec_b64 s[72:73], vcc
	s_cbranch_execz .LBB0_185
	s_and_b32 s0, s85, 0xff
	s_mov_b64 s[76:77], -1
	s_cmp_eq_u32 s0, 0
	s_mov_b64 s[48:49], -1
	s_mov_b64 s[0:1], -1
	s_sleep 1
	s_cbranch_scc1 .LBB0_189
	s_and_saveexec_b64 s[44:45], s[48:49]
	s_cbranch_execz .LBB0_184
	s_branch .LBB0_192

; __device__ __forceinline__ unsigned xb_ld(unsigned* p)              { return __hip_atomic_load(p, __ATOMIC_RELAXED, __HIP_MEMORY_SCOPE_AGENT); }
; __device__ __forceinline__ void xcd_barrier_complete(unsigned* bar, unsigned x, unsigned& nloc, unsigned& nx) {
;     ...
;     for (;;) {
;         sum = 0u; cnt = 0u; mine = 0u;
; #pragma unroll
;         for (unsigned j = 0; j < 16; ++j) { const unsigned c = xb_ld(&bar[XB_XCNT(j)]); sum += c; cnt += (c > 0u) ? 1u : 0u; mine = (j == x) ? c : mine; }
;         if (sum == G) break;
;         __builtin_amdgcn_s_sleep(1);
;         if ((++sp & 255u) == 0u) { if (xb_ld(&bar[XB_TMO])) break; if (sp > XB_SPIN_CAP) { atomicAdd(&bar[XB_TMO], 1u); break; } }
.LBB0_348:
	v_mov_b32_e32 v17, 0
	s_waitcnt lgkmcnt(0)
	global_load_dword v0, v17, s[8:9] sc1
	global_load_dword v2, v17, s[10:11] sc1
	global_load_dword v3, v17, s[12:13] sc1
	global_load_dword v4, v17, s[14:15] sc1
	global_load_dword v5, v17, s[16:17] sc1
	global_load_dword v6, v17, s[18:19] sc1
	global_load_dword v7, v17, s[20:21] sc1
	global_load_dword v8, v17, s[22:23] sc1
	global_load_dword v9, v17, s[24:25] sc1
	global_load_dword v10, v17, s[26:27] sc1
	global_load_dword v11, v17, s[28:29] sc1
	global_load_dword v12, v17, s[30:31] sc1
	global_load_dword v13, v17, s[34:35] sc1
	global_load_dword v14, v17, s[36:37] sc1
	global_load_dword v15, v17, s[40:41] sc1
	global_load_dword v16, v17, s[42:43] sc1
	v_readlane_b32 s0, v252, 38
	s_or_b64 s[76:77], s[76:77], exec
	s_or_b64 s[72:73], s[72:73], exec
	s_waitcnt vmcnt(0)
	v_add_u32_e32 v17, v2, v0
	v_add_u32_e32 v17, v17, v3
	v_add_u32_e32 v17, v17, v4
	v_add_u32_e32 v17, v17, v5
	v_add_u32_e32 v17, v17, v6
	v_add_u32_e32 v17, v17, v7
	v_add_u32_e32 v17, v17, v8
	v_add_u32_e32 v17, v17, v9
	v_add_u32_e32 v17, v17, v10
	v_add_u32_e32 v17, v17, v11
	v_add_u32_e32 v17, v17, v12
	v_add_u32_e32 v17, v17, v13
	v_add_u32_e32 v17, v17, v14
	v_add_u32_e32 v17, v17, v15
	v_add_u32_e32 v17, v17, v16
	v_cmp_ne_u32_e32 vcc, s0, v17
	s_and_saveexec_b64 s[4:5], vcc
	s_cbranch_execz .LBB0_347
	s_and_b32 s0, s55, 0xff
	s_mov_b64 s[90:91], -1
	s_cmp_eq_u32 s0, 0
	s_mov_b64 s[48:49], -1
	s_mov_b64 s[0:1], -1
	s_sleep 1
	s_cbranch_scc1 .LBB0_351
	s_and_saveexec_b64 s[44:45], s[48:49]
	s_cbranch_execz .LBB0_346
	s_branch .LBB0_354

; __device__ __forceinline__ unsigned xb_ld(unsigned* p)              { return __hip_atomic_load(p, __ATOMIC_RELAXED, __HIP_MEMORY_SCOPE_AGENT); }
; __device__ __forceinline__ void xcd_barrier_complete(unsigned* bar, unsigned x, unsigned& nloc, unsigned& nx) {
;     ...
;     for (;;) {
;         sum = 0u; cnt = 0u; mine = 0u;
; #pragma unroll
;         for (unsigned j = 0; j < 16; ++j) { const unsigned c = xb_ld(&bar[XB_XCNT(j)]); sum += c; cnt += (c > 0u) ? 1u : 0u; mine = (j == x) ? c : mine; }
;         if (sum == G) break;
;         __builtin_amdgcn_s_sleep(1);
;         if ((++sp & 255u) == 0u) { if (xb_ld(&bar[XB_TMO])) break; if (sp > XB_SPIN_CAP) { atomicAdd(&bar[XB_TMO], 1u); break; } }
.LBB0_435:
	v_mov_b32_e32 v17, 0
	s_waitcnt lgkmcnt(0)
	global_load_dword v0, v17, s[8:9] sc1
	global_load_dword v2, v17, s[10:11] sc1
	global_load_dword v3, v17, s[12:13] sc1
	global_load_dword v4, v17, s[14:15] sc1
	global_load_dword v5, v17, s[16:17] sc1
	global_load_dword v6, v17, s[18:19] sc1
	global_load_dword v7, v17, s[20:21] sc1
	global_load_dword v8, v17, s[22:23] sc1
	global_load_dword v9, v17, s[24:25] sc1
	global_load_dword v10, v17, s[26:27] sc1
	global_load_dword v11, v17, s[28:29] sc1
	global_load_dword v12, v17, s[30:31] sc1
	global_load_dword v13, v17, s[34:35] sc1
	global_load_dword v14, v17, s[36:37] sc1
	global_load_dword v15, v17, s[42:43] sc1
	global_load_dword v16, v17, s[52:53] sc1
	v_readlane_b32 s0, v252, 38
	s_or_b64 s[90:91], s[90:91], exec
	s_or_b64 s[76:77], s[76:77], exec
	s_waitcnt vmcnt(0)
	v_add_u32_e32 v17, v2, v0
	v_add_u32_e32 v17, v17, v3
	v_add_u32_e32 v17, v17, v4
	v_add_u32_e32 v17, v17, v5
	v_add_u32_e32 v17, v17, v6
	v_add_u32_e32 v17, v17, v7
	v_add_u32_e32 v17, v17, v8
	v_add_u32_e32 v17, v17, v9
	v_add_u32_e32 v17, v17, v10
	v_add_u32_e32 v17, v17, v11
	v_add_u32_e32 v17, v17, v12
	v_add_u32_e32 v17, v17, v13
	v_add_u32_e32 v17, v17, v14
	v_add_u32_e32 v17, v17, v15
	v_add_u32_e32 v17, v17, v16
	v_cmp_ne_u32_e32 vcc, s0, v17
	s_and_saveexec_b64 s[4:5], vcc
	s_cbranch_execz .LBB0_434
	s_and_b32 s0, s84, 0xff
	s_mov_b64 s[94:95], -1
	s_cmp_eq_u32 s0, 0
	s_mov_b64 s[48:49], -1
	s_mov_b64 s[0:1], -1
	s_sleep 1
	s_cbranch_scc1 .LBB0_438
	s_and_saveexec_b64 s[44:45], s[48:49]
	s_cbranch_execz .LBB0_433
	s_branch .LBB0_441

; __device__ __forceinline__ unsigned xb_ld(unsigned* p)              { return __hip_atomic_load(p, __ATOMIC_RELAXED, __HIP_MEMORY_SCOPE_AGENT); }
; __device__ __forceinline__ void xcd_barrier_complete(unsigned* bar, unsigned x, unsigned& nloc, unsigned& nx) {
;     ...
;     for (;;) {
;         sum = 0u; cnt = 0u; mine = 0u;
; #pragma unroll
;         for (unsigned j = 0; j < 16; ++j) { const unsigned c = xb_ld(&bar[XB_XCNT(j)]); sum += c; cnt += (c > 0u) ? 1u : 0u; mine = (j == x) ? c : mine; }
;         if (sum == G) break;
;         __builtin_amdgcn_s_sleep(1);
;         if ((++sp & 255u) == 0u) { if (xb_ld(&bar[XB_TMO])) break; if (sp > XB_SPIN_CAP) { atomicAdd(&bar[XB_TMO], 1u); break; } }
.LBB0_626:
	v_mov_b32_e32 v17, 0
	s_waitcnt lgkmcnt(0)
	global_load_dword v0, v17, s[8:9] sc1
	global_load_dword v2, v17, s[10:11] sc1
	global_load_dword v3, v17, s[12:13] sc1
	global_load_dword v4, v17, s[14:15] sc1
	global_load_dword v5, v17, s[16:17] sc1
	global_load_dword v6, v17, s[18:19] sc1
	global_load_dword v7, v17, s[20:21] sc1
	global_load_dword v8, v17, s[22:23] sc1
	global_load_dword v9, v17, s[24:25] sc1
	global_load_dword v10, v17, s[26:27] sc1
	global_load_dword v11, v17, s[28:29] sc1
	global_load_dword v12, v17, s[30:31] sc1
	global_load_dword v13, v17, s[34:35] sc1
	global_load_dword v14, v17, s[36:37] sc1
	global_load_dword v15, v17, s[60:61] sc1
	global_load_dword v16, v17, s[72:73] sc1
	v_readlane_b32 s0, v252, 38
	s_or_b64 s[96:97], s[96:97], exec
	s_or_b64 s[94:95], s[94:95], exec
	s_waitcnt vmcnt(0)
	v_add_u32_e32 v17, v2, v0
	v_add_u32_e32 v17, v17, v3
	v_add_u32_e32 v17, v17, v4
	v_add_u32_e32 v17, v17, v5
	v_add_u32_e32 v17, v17, v6
	v_add_u32_e32 v17, v17, v7
	v_add_u32_e32 v17, v17, v8
	v_add_u32_e32 v17, v17, v9
	v_add_u32_e32 v17, v17, v10
	v_add_u32_e32 v17, v17, v11
	v_add_u32_e32 v17, v17, v12
	v_add_u32_e32 v17, v17, v13
	v_add_u32_e32 v17, v17, v14
	v_add_u32_e32 v17, v17, v15
	v_add_u32_e32 v17, v17, v16
	v_cmp_ne_u32_e32 vcc, s0, v17
	s_and_saveexec_b64 s[4:5], vcc
	s_cbranch_execz .LBB0_625
	s_and_b32 s44, s55, 0xff
	s_mov_b64 s[0:1], -1
	s_cmp_eq_u32 s44, 0
	s_mov_b64 s[44:45], -1
	s_mov_b64 s[48:49], -1
	s_sleep 1
	s_cbranch_scc1 .LBB0_629
	s_and_saveexec_b64 s[84:85], s[44:45]
	s_cbranch_execz .LBB0_624
	s_branch .LBB0_632

; __device__ __forceinline__ unsigned xb_ld(unsigned* p)              { return __hip_atomic_load(p, __ATOMIC_RELAXED, __HIP_MEMORY_SCOPE_AGENT); }
; __device__ __forceinline__ void xcd_barrier_complete(unsigned* bar, unsigned x, unsigned& nloc, unsigned& nx) {
;     ...
;     for (;;) {
;         sum = 0u; cnt = 0u; mine = 0u;
; #pragma unroll
;         for (unsigned j = 0; j < 16; ++j) { const unsigned c = xb_ld(&bar[XB_XCNT(j)]); sum += c; cnt += (c > 0u) ? 1u : 0u; mine = (j == x) ? c : mine; }
;         if (sum == G) break;
;         __builtin_amdgcn_s_sleep(1);
;         if ((++sp & 255u) == 0u) { if (xb_ld(&bar[XB_TMO])) break; if (sp > XB_SPIN_CAP) { atomicAdd(&bar[XB_TMO], 1u); break; } }
.LBB0_888:
	v_mov_b32_e32 v17, 0
	s_waitcnt lgkmcnt(0)
	global_load_dword v0, v17, s[8:9] sc1
	global_load_dword v2, v17, s[10:11] sc1
	global_load_dword v3, v17, s[12:13] sc1
	global_load_dword v4, v17, s[14:15] sc1
	global_load_dword v5, v17, s[16:17] sc1
	global_load_dword v6, v17, s[18:19] sc1
	global_load_dword v7, v17, s[20:21] sc1
	global_load_dword v8, v17, s[22:23] sc1
	global_load_dword v9, v17, s[24:25] sc1
	global_load_dword v10, v17, s[26:27] sc1
	global_load_dword v11, v17, s[28:29] sc1
	global_load_dword v12, v17, s[30:31] sc1
	global_load_dword v13, v17, s[34:35] sc1
	global_load_dword v14, v17, s[36:37] sc1
	global_load_dword v15, v17, s[42:43] sc1
	global_load_dword v16, v17, s[52:53] sc1
	v_readlane_b32 s0, v252, 38
	s_or_b64 s[90:91], s[90:91], exec
	s_or_b64 s[76:77], s[76:77], exec
	s_waitcnt vmcnt(0)
	v_add_u32_e32 v17, v2, v0
	v_add_u32_e32 v17, v17, v3
	v_add_u32_e32 v17, v17, v4
	v_add_u32_e32 v17, v17, v5
	v_add_u32_e32 v17, v17, v6
	v_add_u32_e32 v17, v17, v7
	v_add_u32_e32 v17, v17, v8
	v_add_u32_e32 v17, v17, v9
	v_add_u32_e32 v17, v17, v10
	v_add_u32_e32 v17, v17, v11
	v_add_u32_e32 v17, v17, v12
	v_add_u32_e32 v17, v17, v13
	v_add_u32_e32 v17, v17, v14
	v_add_u32_e32 v17, v17, v15
	v_add_u32_e32 v17, v17, v16
	v_cmp_ne_u32_e32 vcc, s0, v17
	s_and_saveexec_b64 s[4:5], vcc
	s_cbranch_execz .LBB0_887
	s_and_b32 s44, s62, 0xff
	s_mov_b64 s[0:1], -1
	s_cmp_eq_u32 s44, 0
	s_mov_b64 s[44:45], -1
	s_mov_b64 s[48:49], -1
	s_sleep 1
	s_cbranch_scc1 .LBB0_891
	s_and_saveexec_b64 s[84:85], s[44:45]
	s_cbranch_execz .LBB0_886
	s_branch .LBB0_894

; __device__ __forceinline__ unsigned xb_ld(unsigned* p)              { return __hip_atomic_load(p, __ATOMIC_RELAXED, __HIP_MEMORY_SCOPE_AGENT); }
; __device__ __forceinline__ void xcd_barrier_complete(unsigned* bar, unsigned x, unsigned& nloc, unsigned& nx) {
;     ...
;     for (;;) {
;         sum = 0u; cnt = 0u; mine = 0u;
; #pragma unroll
;         for (unsigned j = 0; j < 16; ++j) { const unsigned c = xb_ld(&bar[XB_XCNT(j)]); sum += c; cnt += (c > 0u) ? 1u : 0u; mine = (j == x) ? c : mine; }
;         if (sum == G) break;
;         __builtin_amdgcn_s_sleep(1);
;         if ((++sp & 255u) == 0u) { if (xb_ld(&bar[XB_TMO])) break; if (sp > XB_SPIN_CAP) { atomicAdd(&bar[XB_TMO], 1u); break; } }
.LBB0_983:
	v_mov_b32_e32 v17, 0
	s_waitcnt lgkmcnt(0)
	global_load_dword v0, v17, s[8:9] sc1
	global_load_dword v2, v17, s[10:11] sc1
	global_load_dword v3, v17, s[12:13] sc1
	global_load_dword v4, v17, s[14:15] sc1
	global_load_dword v5, v17, s[16:17] sc1
	global_load_dword v6, v17, s[18:19] sc1
	global_load_dword v7, v17, s[20:21] sc1
	global_load_dword v8, v17, s[22:23] sc1
	global_load_dword v9, v17, s[24:25] sc1
	global_load_dword v10, v17, s[26:27] sc1
	global_load_dword v11, v17, s[28:29] sc1
	global_load_dword v12, v17, s[30:31] sc1
	global_load_dword v13, v17, s[34:35] sc1
	global_load_dword v14, v17, s[36:37] sc1
	global_load_dword v15, v17, s[42:43] sc1
	global_load_dword v16, v17, s[52:53] sc1
	v_readlane_b32 s0, v252, 38
	s_or_b64 s[76:77], s[76:77], exec
	s_or_b64 s[72:73], s[72:73], exec
	s_waitcnt vmcnt(0)
	v_add_u32_e32 v17, v2, v0
	v_add_u32_e32 v17, v17, v3
	v_add_u32_e32 v17, v17, v4
	v_add_u32_e32 v17, v17, v5
	v_add_u32_e32 v17, v17, v6
	v_add_u32_e32 v17, v17, v7
	v_add_u32_e32 v17, v17, v8
	v_add_u32_e32 v17, v17, v9
	v_add_u32_e32 v17, v17, v10
	v_add_u32_e32 v17, v17, v11
	v_add_u32_e32 v17, v17, v12
	v_add_u32_e32 v17, v17, v13
	v_add_u32_e32 v17, v17, v14
	v_add_u32_e32 v17, v17, v15
	v_add_u32_e32 v17, v17, v16
	v_cmp_ne_u32_e32 vcc, s0, v17
	s_and_saveexec_b64 s[4:5], vcc
	s_cbranch_execz .LBB0_982
	s_and_b32 s44, s95, 0xff
	s_mov_b64 s[0:1], -1
	s_cmp_eq_u32 s44, 0
	s_mov_b64 s[44:45], -1
	s_mov_b64 s[48:49], -1
	s_sleep 1
	s_cbranch_scc1 .LBB0_986
	s_and_saveexec_b64 s[78:79], s[44:45]
	s_cbranch_execz .LBB0_981
	s_branch .LBB0_989

; __device__ __forceinline__ unsigned xb_ld(unsigned* p)              { return __hip_atomic_load(p, __ATOMIC_RELAXED, __HIP_MEMORY_SCOPE_AGENT); }
; __device__ __forceinline__ void xcd_barrier_complete(unsigned* bar, unsigned x, unsigned& nloc, unsigned& nx) {
;     ...
;     for (;;) {
;         sum = 0u; cnt = 0u; mine = 0u;
; #pragma unroll
;         for (unsigned j = 0; j < 16; ++j) { const unsigned c = xb_ld(&bar[XB_XCNT(j)]); sum += c; cnt += (c > 0u) ? 1u : 0u; mine = (j == x) ? c : mine; }
;         if (sum == G) break;
;         __builtin_amdgcn_s_sleep(1);
;         if ((++sp & 255u) == 0u) { if (xb_ld(&bar[XB_TMO])) break; if (sp > XB_SPIN_CAP) { atomicAdd(&bar[XB_TMO], 1u); break; } }
.LBB0_1044:
	v_mov_b32_e32 v17, 0
	s_waitcnt lgkmcnt(0)
	global_load_dword v0, v17, s[8:9] sc1
	global_load_dword v2, v17, s[10:11] sc1
	global_load_dword v3, v17, s[12:13] sc1
	global_load_dword v4, v17, s[14:15] sc1
	global_load_dword v5, v17, s[16:17] sc1
	global_load_dword v6, v17, s[18:19] sc1
	global_load_dword v7, v17, s[20:21] sc1
	global_load_dword v8, v17, s[22:23] sc1
	global_load_dword v9, v17, s[24:25] sc1
	global_load_dword v10, v17, s[26:27] sc1
	global_load_dword v11, v17, s[28:29] sc1
	global_load_dword v12, v17, s[30:31] sc1
	global_load_dword v13, v17, s[34:35] sc1
	global_load_dword v14, v17, s[36:37] sc1
	global_load_dword v15, v17, s[42:43] sc1
	global_load_dword v16, v17, s[52:53] sc1
	v_readlane_b32 s0, v252, 38
	s_or_b64 s[76:77], s[76:77], exec
	s_or_b64 s[72:73], s[72:73], exec
	s_waitcnt vmcnt(0)
	v_add_u32_e32 v17, v2, v0
	v_add_u32_e32 v17, v17, v3
	v_add_u32_e32 v17, v17, v4
	v_add_u32_e32 v17, v17, v5
	v_add_u32_e32 v17, v17, v6
	v_add_u32_e32 v17, v17, v7
	v_add_u32_e32 v17, v17, v8
	v_add_u32_e32 v17, v17, v9
	v_add_u32_e32 v17, v17, v10
	v_add_u32_e32 v17, v17, v11
	v_add_u32_e32 v17, v17, v12
	v_add_u32_e32 v17, v17, v13
	v_add_u32_e32 v17, v17, v14
	v_add_u32_e32 v17, v17, v15
	v_add_u32_e32 v17, v17, v16
	v_cmp_ne_u32_e32 vcc, s0, v17
	s_and_saveexec_b64 s[4:5], vcc
	s_cbranch_execz .LBB0_1043
	s_and_b32 s44, s94, 0xff
	s_mov_b64 s[0:1], -1
	s_cmp_eq_u32 s44, 0
	s_mov_b64 s[44:45], -1
	s_mov_b64 s[48:49], -1
	s_sleep 1
	s_cbranch_scc1 .LBB0_1047
	s_and_saveexec_b64 s[78:79], s[44:45]
	s_cbranch_execz .LBB0_1042
	s_branch .LBB0_1050

; __device__ __forceinline__ unsigned xb_ld(unsigned* p)              { return __hip_atomic_load(p, __ATOMIC_RELAXED, __HIP_MEMORY_SCOPE_AGENT); }
; __device__ __forceinline__ void xcd_barrier_complete(unsigned* bar, unsigned x, unsigned& nloc, unsigned& nx) {
;     ...
;     for (;;) {
;         sum = 0u; cnt = 0u; mine = 0u;
; #pragma unroll
;         for (unsigned j = 0; j < 16; ++j) { const unsigned c = xb_ld(&bar[XB_XCNT(j)]); sum += c; cnt += (c > 0u) ? 1u : 0u; mine = (j == x) ? c : mine; }
;         if (sum == G) break;
;         __builtin_amdgcn_s_sleep(1);
;         if ((++sp & 255u) == 0u) { if (xb_ld(&bar[XB_TMO])) break; if (sp > XB_SPIN_CAP) { atomicAdd(&bar[XB_TMO], 1u); break; } }
.LBB0_1131:
	v_mov_b32_e32 v17, 0
	s_waitcnt lgkmcnt(0)
	global_load_dword v0, v17, s[6:7] sc1
	global_load_dword v2, v17, s[8:9] sc1
	global_load_dword v3, v17, s[10:11] sc1
	global_load_dword v4, v17, s[12:13] sc1
	global_load_dword v5, v17, s[14:15] sc1
	global_load_dword v6, v17, s[16:17] sc1
	global_load_dword v7, v17, s[18:19] sc1
	global_load_dword v8, v17, s[20:21] sc1
	global_load_dword v9, v17, s[22:23] sc1
	global_load_dword v10, v17, s[24:25] sc1
	global_load_dword v11, v17, s[26:27] sc1
	global_load_dword v12, v17, s[28:29] sc1
	global_load_dword v13, v17, s[30:31] sc1
	global_load_dword v14, v17, s[34:35] sc1
	global_load_dword v15, v17, s[38:39] sc1
	global_load_dword v16, v17, s[40:41] sc1
	v_readlane_b32 s0, v252, 38
	s_or_b64 s[60:61], s[60:61], exec
	s_or_b64 s[54:55], s[54:55], exec
	s_waitcnt vmcnt(0)
	v_add_u32_e32 v17, v2, v0
	v_add_u32_e32 v17, v17, v3
	v_add_u32_e32 v17, v17, v4
	v_add_u32_e32 v17, v17, v5
	v_add_u32_e32 v17, v17, v6
	v_add_u32_e32 v17, v17, v7
	v_add_u32_e32 v17, v17, v8
	v_add_u32_e32 v17, v17, v9
	v_add_u32_e32 v17, v17, v10
	v_add_u32_e32 v17, v17, v11
	v_add_u32_e32 v17, v17, v12
	v_add_u32_e32 v17, v17, v13
	v_add_u32_e32 v17, v17, v14
	v_add_u32_e32 v17, v17, v15
	v_add_u32_e32 v17, v17, v16
	v_cmp_ne_u32_e32 vcc, s0, v17
	s_and_saveexec_b64 s[72:73], vcc
	s_cbranch_execz .LBB0_1130
	s_and_b32 s44, s78, 0xff
	s_mov_b64 s[0:1], -1
	s_cmp_eq_u32 s44, 0
	s_mov_b64 s[44:45], -1
	s_mov_b64 s[48:49], -1
	s_sleep 1
	s_cbranch_scc1 .LBB0_1134
	s_and_saveexec_b64 s[76:77], s[44:45]
	s_cbranch_execz .LBB0_1129
	s_branch .LBB0_1137
